# mixer-A PV2 row-sum chain with all packed adds split into scalar pairs (on the aligned, rotated loop)
# speedup vs baseline: 1.0076x; 1.0031x over previous
.Lattn_dma_done_a:
	v_exp_f32_e32 v172, v128
	v_exp_f32_e32 v170, v129
	v_exp_f32_e32 v176, v130
	v_exp_f32_e32 v168, v131
	v_exp_f32_e32 v182, v132
	v_exp_f32_e32 v178, v133
	v_exp_f32_e32 v188, v134
	v_exp_f32_e32 v174, v135
	v_exp_f32_e32 v192, v136
	v_exp_f32_e32 v186, v137
	v_exp_f32_e32 v194, v138
	v_exp_f32_e32 v180, v139
	v_exp_f32_e32 v196, v140
	v_exp_f32_e32 v190, v141
	v_exp_f32_e32 v198, v142
	v_exp_f32_e32 v184, v143
	v_cvt_pk_bf16_f32 v144, v173, v169
	v_cvt_pk_bf16_f32 v145, v177, v171
	v_cvt_pk_bf16_f32 v146, v183, v175
	v_cvt_pk_bf16_f32 v147, v189, v179
	v_cvt_pk_bf16_f32 v148, v193, v181
	v_cvt_pk_bf16_f32 v149, v195, v187
	v_cvt_pk_bf16_f32 v150, v197, v185
	v_cvt_pk_bf16_f32 v151, v199, v191
	v_cvt_pk_bf16_f32 v128, v172, v170
	v_cvt_pk_bf16_f32 v129, v176, v168
	v_cvt_pk_bf16_f32 v130, v182, v178
	v_cvt_pk_bf16_f32 v131, v188, v174
	v_cvt_pk_bf16_f32 v132, v192, v186
	v_cvt_pk_bf16_f32 v133, v194, v180
	v_cvt_pk_bf16_f32 v134, v196, v190
	v_cvt_pk_bf16_f32 v135, v198, v184
	v_add3_u32 v160, s7, v162, v160
	v_xad_u32 v252, v163, 64, s7
	v_add_u32_e32 v203, s7, v203
	v_add_u32_e32 v205, s7, v206
	ds_read_b64_tr_b16 v[136:137], v160 offset:32768
	ds_read_b64_tr_b16 v[138:139], v160 offset:34816
	ds_read_b64_tr_b16 v[140:141], v160 offset:36864
	ds_read_b64_tr_b16 v[142:143], v160 offset:38912
	ds_read_b64_tr_b16 v[152:153], v252 offset:32768
	ds_read_b64_tr_b16 v[154:155], v252 offset:34816
	ds_read_b64_tr_b16 v[156:157], v252 offset:36864
	ds_read_b64_tr_b16 v[158:159], v252 offset:38912
	ds_read_b64_tr_b16 v[208:209], v203 offset:32768
	ds_read_b64_tr_b16 v[210:211], v203 offset:34816
	ds_read_b64_tr_b16 v[212:213], v203 offset:36864
	ds_read_b64_tr_b16 v[214:215], v203 offset:38912
	ds_read_b64_tr_b16 v[216:217], v205 offset:32768
	ds_read_b64_tr_b16 v[218:219], v205 offset:34816
	ds_read_b64_tr_b16 v[220:221], v205 offset:36864
	ds_read_b64_tr_b16 v[222:223], v205 offset:38912
	s_waitcnt lgkmcnt(14)
	v_mfma_f32_32x32x16_bf16 v[64:79], v[144:147], v[136:139], v[64:79]
	v_mfma_f32_32x32x16_bf16 v[0:15], v[128:131], v[136:139], v[0:15]
	s_waitcnt lgkmcnt(10)
	v_mfma_f32_32x32x16_bf16 v[80:95], v[144:147], v[152:155], v[80:95]
	v_mfma_f32_32x32x16_bf16 v[16:31], v[128:131], v[152:155], v[16:31]
	s_waitcnt lgkmcnt(6)
	v_mfma_f32_32x32x16_bf16 v[96:111], v[144:147], v[208:211], v[96:111]
	v_mfma_f32_32x32x16_bf16 v[32:47], v[128:131], v[208:211], v[32:47]
	s_waitcnt lgkmcnt(2)
	v_mfma_f32_32x32x16_bf16 v[112:127], v[144:147], v[216:219], v[112:127]
	v_mfma_f32_32x32x16_bf16 v[48:63], v[128:131], v[216:219], v[48:63]
	v_mfma_f32_32x32x16_bf16 v[64:79], v[148:151], v[140:143], v[64:79]
	v_mfma_f32_32x32x16_bf16 v[0:15], v[132:135], v[140:143], v[0:15]
	v_mfma_f32_32x32x16_bf16 v[80:95], v[148:151], v[156:159], v[80:95]
	v_mfma_f32_32x32x16_bf16 v[16:31], v[132:135], v[156:159], v[16:31]
	v_mfma_f32_32x32x16_bf16 v[96:111], v[148:151], v[212:215], v[96:111]
	v_mfma_f32_32x32x16_bf16 v[32:47], v[132:135], v[212:215], v[32:47]
	s_waitcnt lgkmcnt(0)
	v_mfma_f32_32x32x16_bf16 v[112:127], v[148:151], v[220:223], v[112:127]
	v_mfma_f32_32x32x16_bf16 v[48:63], v[132:135], v[220:223], v[48:63]
	ds_read_b128 v[128:131], v207 offset:4096
	ds_read_b128 v[132:135], v224
	ds_read_b128 v[136:139], v225 offset:4096
	ds_read_b128 v[140:143], v226
	s_waitcnt lgkmcnt(2)
	v_mfma_f32_32x32x16_bf16 v[144:159], v[128:131], v[132:135], 0
	ds_read_b128 v[128:131], v227 offset:4096
	ds_read_b128 v[132:135], v228
	s_waitcnt lgkmcnt(2)
	v_mfma_f32_32x32x16_bf16 v[144:159], v[136:139], v[140:143], v[144:159]
	ds_read_b128 v[136:139], v230 offset:4096
	ds_read_b128 v[140:143], v232
	s_waitcnt lgkmcnt(2)
	v_mfma_f32_32x32x16_bf16 v[144:159], v[128:131], v[132:135], v[144:159]
	ds_read_b128 v[128:131], v207 offset:12288
	ds_read_b128 v[132:135], v224 offset:4096
	s_waitcnt lgkmcnt(2)
	v_mfma_f32_32x32x16_bf16 v[144:159], v[136:139], v[140:143], v[144:159]
	ds_read_b128 v[208:211], v225 offset:12288
	ds_read_b128 v[212:215], v226 offset:4096
	s_waitcnt lgkmcnt(2)
	v_mfma_f32_32x32x16_bf16 v[128:143], v[128:131], v[132:135], 0
	s_nop 7
	v_exp_f32_e32 v229, v144
	v_exp_f32_e32 v145, v145
	v_exp_f32_e32 v231, v146
	v_exp_f32_e32 v147, v147
	ds_read_b128 v[216:219], v227 offset:12288
	ds_read_b128 v[220:223], v228 offset:4096
	s_waitcnt lgkmcnt(2)
	v_mfma_f32_32x32x16_bf16 v[128:143], v[208:211], v[212:215], v[128:143]
	v_exp_f32_e32 v233, v148
	v_exp_f32_e32 v235, v149
	v_exp_f32_e32 v237, v150
	v_exp_f32_e32 v239, v151
	ds_read_b128 v[148:151], v230 offset:12288
	ds_read_b128 v[208:211], v232 offset:4096
	s_waitcnt lgkmcnt(2)
	v_mfma_f32_32x32x16_bf16 v[128:143], v[216:219], v[220:223], v[128:143]
	v_exp_f32_e32 v241, v152
	v_exp_f32_e32 v243, v153
	v_exp_f32_e32 v245, v154
	v_exp_f32_e32 v247, v155
	s_waitcnt lgkmcnt(0)
	v_mfma_f32_32x32x16_bf16 v[128:143], v[148:151], v[208:211], v[128:143]
	v_exp_f32_e32 v249, v156
	v_exp_f32_e32 v251, v157
	v_exp_f32_e32 v207, v158
	v_exp_f32_e32 v163, v159
	s_nop 7
	v_exp_f32_e32 v228, v128
	v_exp_f32_e32 v146, v129
	v_exp_f32_e32 v230, v130
	v_exp_f32_e32 v144, v131
	v_exp_f32_e32 v232, v132
	v_exp_f32_e32 v238, v133
	v_exp_f32_e32 v236, v134
	v_exp_f32_e32 v234, v135
	v_exp_f32_e32 v240, v136
	v_exp_f32_e32 v246, v137
	v_exp_f32_e32 v244, v138
	v_exp_f32_e32 v242, v139
	v_exp_f32_e32 v248, v140
	v_exp_f32_e32 v162, v141
	v_exp_f32_e32 v206, v142
	v_exp_f32_e32 v250, v143
	v_cvt_pk_bf16_f32 v148, v229, v145
	v_cvt_pk_bf16_f32 v149, v231, v147
	v_cvt_pk_bf16_f32 v150, v233, v235
	v_cvt_pk_bf16_f32 v151, v237, v239
	v_cvt_pk_bf16_f32 v152, v241, v243
	v_cvt_pk_bf16_f32 v153, v245, v247
	v_cvt_pk_bf16_f32 v154, v249, v251
	v_cvt_pk_bf16_f32 v155, v207, v163
	v_cvt_pk_bf16_f32 v128, v228, v146
	v_cvt_pk_bf16_f32 v129, v230, v144
	v_cvt_pk_bf16_f32 v130, v232, v238
	v_cvt_pk_bf16_f32 v131, v236, v234
	v_cvt_pk_bf16_f32 v132, v240, v246
	v_cvt_pk_bf16_f32 v133, v244, v242
	v_cvt_pk_bf16_f32 v134, v248, v162
	v_cvt_pk_bf16_f32 v135, v206, v250
	s_addk_i32 s5, 0x4000
	s_add_i32 s4, s4, 0x10000
	s_and_b32 s7, s5, 0x4000
	ds_read_b64_tr_b16 v[136:137], v160 offset:40960
	ds_read_b64_tr_b16 v[138:139], v160 offset:43008
	ds_read_b64_tr_b16 v[140:141], v160 offset:45056
	ds_read_b64_tr_b16 v[142:143], v160 offset:47104
	ds_read_b64_tr_b16 v[156:157], v252 offset:40960
	ds_read_b64_tr_b16 v[158:159], v252 offset:43008
	ds_read_b64_tr_b16 v[208:209], v252 offset:45056
	ds_read_b64_tr_b16 v[210:211], v252 offset:47104
	ds_read_b64_tr_b16 v[212:213], v203 offset:40960
	ds_read_b64_tr_b16 v[214:215], v203 offset:43008
	ds_read_b64_tr_b16 v[216:217], v203 offset:45056
	ds_read_b64_tr_b16 v[218:219], v203 offset:47104
	ds_read_b64_tr_b16 v[220:221], v205 offset:40960
	ds_read_b64_tr_b16 v[222:223], v205 offset:43008
	ds_read_b64_tr_b16 v[224:225], v205 offset:45056
	ds_read_b64_tr_b16 v[226:227], v205 offset:47104
	s_waitcnt lgkmcnt(14)
	v_mfma_f32_32x32x16_bf16 v[64:79], v[148:151], v[136:139], v[64:79]
	v_mfma_f32_32x32x16_bf16 v[0:15], v[128:131], v[136:139], v[0:15]
	s_waitcnt lgkmcnt(10)
	v_mfma_f32_32x32x16_bf16 v[80:95], v[148:151], v[156:159], v[80:95]
	v_mfma_f32_32x32x16_bf16 v[16:31], v[128:131], v[156:159], v[16:31]
	s_waitcnt lgkmcnt(6)
	v_mfma_f32_32x32x16_bf16 v[96:111], v[148:151], v[212:215], v[96:111]
	v_mfma_f32_32x32x16_bf16 v[32:47], v[128:131], v[212:215], v[32:47]
	s_waitcnt lgkmcnt(2)
	v_mfma_f32_32x32x16_bf16 v[112:127], v[148:151], v[220:223], v[112:127]
	v_mfma_f32_32x32x16_bf16 v[48:63], v[128:131], v[220:223], v[48:63]
	v_add_f32_e64 v128, v172, v176
	v_add_f32_e64 v129, v173, v177
	v_add_f32_e64 v130, v168, v170
	v_add_f32_e64 v131, v169, v171
	v_add_f32_e64 v136, v182, v188
	v_add_f32_e64 v137, v183, v189
	v_add_f32_e64 v128, v136, v128
	v_add_f32_e64 v129, v137, v129
	v_add_f32_e64 v136, v174, v178
	v_add_f32_e64 v137, v175, v179
	v_add_f32_e64 v138, v232, v236
	v_add_f32_e64 v139, v233, v237
	v_add_f32_e64 v130, v136, v130
	v_add_f32_e64 v131, v137, v131
	v_add_f32_e64 v136, v192, v194
	v_add_f32_e64 v137, v193, v195
	v_mfma_f32_32x32x16_bf16 v[64:79], v[152:155], v[140:143], v[64:79]
	v_add_f32_e64 v128, v136, v128
	v_add_f32_e64 v129, v137, v129
	v_add_f32_e64 v136, v180, v186
	v_add_f32_e64 v137, v181, v187
	v_add_f32_e64 v130, v136, v130
	v_add_f32_e64 v131, v137, v131
	v_add_f32_e64 v136, v196, v198
	v_add_f32_e64 v137, v197, v199
	s_nop 0
	v_add_f32_e64 v128, v136, v128
	v_add_f32_e64 v129, v137, v129
	v_add_f32_e64 v136, v184, v190
	v_add_f32_e64 v137, v185, v191
	v_mfma_f32_32x32x16_bf16 v[0:15], v[132:135], v[140:143], v[0:15]
	v_add_f32_e64 v130, v136, v130
	v_add_f32_e64 v131, v137, v131
	v_add_f32_e64 v136, v144, v146
	v_add_f32_e64 v137, v145, v147
	v_add_f32_e64 v128, v128, v130
	v_add_f32_e64 v129, v129, v131
	v_add_f32_e64 v130, v228, v230
	v_add_f32_e64 v131, v229, v231
	v_add_f32_e64 v128, v166, v128
	v_add_f32_e64 v129, v167, v129
	v_mfma_f32_32x32x16_bf16 v[80:95], v[152:155], v[208:211], v[80:95]
	v_add_f32_e64 v130, v138, v130
	v_add_f32_e64 v131, v139, v131
	v_add_f32_e64 v138, v234, v238
	v_add_f32_e64 v139, v235, v239
	v_add_f32_e64 v136, v138, v136
	v_add_f32_e64 v137, v139, v137
	v_add_f32_e64 v138, v240, v244
	v_add_f32_e64 v139, v241, v245
	s_nop 0
	v_add_f32_e64 v130, v138, v130
	v_add_f32_e64 v131, v139, v131
	v_mfma_f32_32x32x16_bf16 v[16:31], v[132:135], v[208:211], v[16:31]
	v_add_f32_e64 v138, v242, v246
	v_add_f32_e64 v139, v243, v247
	v_add_f32_e64 v136, v138, v136
	v_add_f32_e64 v137, v139, v137
	v_add_f32_e64 v138, v248, v206
	v_add_f32_e64 v139, v249, v207
	v_add_f32_e64 v130, v138, v130
	v_add_f32_e64 v131, v139, v131
	v_add_f32_e64 v138, v250, v162
	v_add_f32_e64 v139, v251, v163
	v_mfma_f32_32x32x16_bf16 v[96:111], v[152:155], v[216:219], v[96:111]
	v_add_f32_e64 v136, v138, v136
	v_add_f32_e64 v137, v139, v137
	v_add_f32_e64 v130, v130, v136
	v_add_f32_e64 v131, v131, v137
	v_add_f32_e64 v166, v128, v130
	v_add_f32_e64 v167, v129, v131
	v_mfma_f32_32x32x16_bf16 v[32:47], v[132:135], v[216:219], v[32:47]
	s_waitcnt lgkmcnt(0)
	v_mfma_f32_32x32x16_bf16 v[112:127], v[152:155], v[224:227], v[112:127]
	v_mfma_f32_32x32x16_bf16 v[48:63], v[132:135], v[224:227], v[48:63]
	s_waitcnt vmcnt(0)
	s_cmp_eq_u32 s4, 0x400000
	s_cbranch_scc0 .Lattn_head_a
	s_barrier
